# E34 PH1 softmax epilogue: eight serialized q-row sum loads issued together at the first site (on top of E33)
# speedup vs baseline: 1.0078x; 1.0026x over previous
;     __device__ __forceinline__ void operator()(const Acc& acc, const Unit& u, int wr, int wc, int fr, int fq) const {
;     ...
;         for (int ai = 0; ai < 2; ++ai)
; #pragma unroll
;             for (int m = 0; m < 4; ++m) {
;                 const int rl = ai * 128 + wr * 64 + m * 16 + fr;
;                 rq[ai][m] = __builtin_amdgcn_rsqf(ssq[u.pm * 256 + rl] * (1.f / 256.f) + EPS) * (0.0625f * LOG2E);
;                 float v = -3.0e38f;
; #pragma unroll
;                 for (int bj = 0; bj < 2; ++bj)
; #pragma unroll
;                     for (int n = 0; n < 2; ++n)
; #pragma unroll
;                         for (int j = 0; j < 4; ++j) v = fmaxf(v, acc[ai][bj][m][n][j]);
;                 v *= rq[ai][m];
;                 v = fmaxf(v, xshfl<16>(v)); v = fmaxf(v, xshfl<32>(v));
;                 if (fq == 0) EXm[rl * 4 + wc] = v;
;             }
.LBB0_968:
	s_add_i32 s22, s18, s47
	s_ashr_i32 s23, s22, 31
	s_mov_b64 s[20:21], s[2:3]
	s_lshl_b64 s[22:23], s[22:23], 16
	s_add_u32 s22, s20, s22
	s_addc_u32 s23, s21, s23
	s_lshl_b32 s13, s55, 8
	v_add_u32_e32 v140, s13, v168
	v_ashrrev_i32_e32 v141, 31, v140
	v_lshl_add_u64 v[142:143], v[140:141], 2, s[22:23]
	s_mov_b32 s19, 0xff00000
	s_mov_b64 s[22:23], 0xff00000
	v_lshl_add_u64 v[142:143], v[142:143], 0, s[22:23]
	global_load_dword v144, v[142:143], off
	global_load_dword v166, v[142:143], off offset:64
	global_load_dword v155, v[142:143], off offset:128
	global_load_dword v154, v[142:143], off offset:192
	global_load_dword v153, v[142:143], off offset:512
	global_load_dword v152, v[142:143], off offset:576
	global_load_dword v151, v[142:143], off offset:640
	global_load_dword v150, v[142:143], off offset:704
	v_max3_f32 v145, v124, s45, v125
	v_max3_f32 v145, v145, v126, v127
	v_max3_f32 v145, v145, v120, v121
	v_max3_f32 v145, v145, v122, v123
	v_max3_f32 v145, v145, v116, v117
	v_max3_f32 v145, v145, v118, v119
	v_max3_f32 v145, v145, v112, v113
	v_max3_f32 v145, v145, v114, v115
	s_waitcnt vmcnt(0)
	v_fmamk_f32 v144, v144, 0x3b800000, v212
	v_rsq_f32_e32 v144, v144
	s_nop 0
	v_mul_f32_e32 v149, 0x3db8aa3b, v144
	v_mul_f32_e32 v144, v145, v149
	ds_swizzle_b32 v145, v144 offset:swizzle(SWAP,16)
	s_waitcnt lgkmcnt(0)
	v_max_f32_e32 v145, v145, v145
	v_max_f32_e32 v144, v144, v145
	v_mov_b32_e32 v145, v144
	v_mov_b32_e32 v146, v144
	s_nop 1
	v_permlane32_swap_b32_e32 v145, v146
	s_and_saveexec_b64 s[22:23], s[0:1]
	s_cbranch_execz .LBB0_970
	v_cmp_eq_u32_e32 vcc, 0, v214
	v_max_f32_e32 v144, v144, v144
	s_nop 0
	v_cndmask_b32_e32 v145, v145, v146, vcc
	v_max_f32_e32 v145, v145, v145
	v_max_f32_e32 v144, v144, v145
	v_add_u32_e32 v145, s48, v170
	ds_write_b32 v145, v144
.LBB0_970:
	s_or_b64 exec, exec, s[22:23]
	v_max3_f32 v145, v108, s45, v109
	v_max3_f32 v145, v145, v110, v111
	v_max3_f32 v145, v145, v104, v105
	v_max3_f32 v145, v145, v106, v107
	v_max3_f32 v145, v145, v100, v101
	v_max3_f32 v145, v145, v102, v103
	v_max3_f32 v145, v145, v96, v97
	v_max3_f32 v145, v145, v98, v99
	s_waitcnt vmcnt(0)
	v_fmamk_f32 v144, v166, 0x3b800000, v212
	v_rsq_f32_e32 v144, v144
	s_nop 0
	v_mul_f32_e32 v166, 0x3db8aa3b, v144
	v_mul_f32_e32 v144, v145, v166
	ds_swizzle_b32 v145, v144 offset:swizzle(SWAP,16)
	s_waitcnt lgkmcnt(0)
	v_max_f32_e32 v145, v145, v145
	v_max_f32_e32 v144, v144, v145
	v_mov_b32_e32 v145, v144
	v_mov_b32_e32 v146, v144
	s_nop 1
	v_permlane32_swap_b32_e32 v145, v146
	s_and_saveexec_b64 s[22:23], s[0:1]
	s_cbranch_execz .LBB0_972
	v_cmp_eq_u32_e32 vcc, 0, v214
	v_max_f32_e32 v144, v144, v144
	s_nop 0
	v_cndmask_b32_e32 v145, v145, v146, vcc
	v_max_f32_e32 v145, v145, v145
	v_max_f32_e32 v144, v144, v145
	v_add_u32_e32 v145, s48, v172
	ds_write_b32 v145, v144
.LBB0_972:
	s_or_b64 exec, exec, s[22:23]
	v_max3_f32 v145, v92, s45, v93
	v_max3_f32 v145, v145, v94, v95
	v_max3_f32 v145, v145, v88, v89
	v_max3_f32 v145, v145, v90, v91
	v_max3_f32 v145, v145, v84, v85
	v_max3_f32 v145, v145, v86, v87
	v_max3_f32 v145, v145, v80, v81
	v_max3_f32 v145, v145, v82, v83
	s_waitcnt vmcnt(0)
	v_fmamk_f32 v144, v155, 0x3b800000, v212
	v_rsq_f32_e32 v144, v144
	s_nop 0
	v_mul_f32_e32 v155, 0x3db8aa3b, v144
	v_mul_f32_e32 v144, v145, v155
	ds_swizzle_b32 v145, v144 offset:swizzle(SWAP,16)
	s_waitcnt lgkmcnt(0)
	v_max_f32_e32 v145, v145, v145
	v_max_f32_e32 v144, v144, v145
	v_mov_b32_e32 v145, v144
	v_mov_b32_e32 v146, v144
	s_nop 1
	v_permlane32_swap_b32_e32 v145, v146
	s_and_saveexec_b64 s[22:23], s[0:1]
	s_cbranch_execz .LBB0_974
	v_cmp_eq_u32_e32 vcc, 0, v214
	v_max_f32_e32 v144, v144, v144
	s_nop 0
	v_cndmask_b32_e32 v145, v145, v146, vcc
	v_max_f32_e32 v145, v145, v145
	v_max_f32_e32 v144, v144, v145
	v_add_u32_e32 v145, s48, v174
	ds_write_b32 v145, v144
.LBB0_974:
	s_or_b64 exec, exec, s[22:23]
	v_max3_f32 v145, v76, s45, v77
	v_max3_f32 v145, v145, v78, v79
	v_max3_f32 v145, v145, v72, v73
	v_max3_f32 v145, v145, v74, v75
	v_max3_f32 v145, v145, v68, v69
	v_max3_f32 v145, v145, v70, v71
	v_max3_f32 v145, v145, v64, v65
	v_max3_f32 v145, v145, v66, v67
	s_waitcnt vmcnt(0)
	v_fmamk_f32 v144, v154, 0x3b800000, v212
	v_rsq_f32_e32 v144, v144
	s_nop 0
	v_mul_f32_e32 v154, 0x3db8aa3b, v144
	v_mul_f32_e32 v144, v145, v154
	ds_swizzle_b32 v145, v144 offset:swizzle(SWAP,16)
	s_waitcnt lgkmcnt(0)
	v_max_f32_e32 v145, v145, v145
	v_max_f32_e32 v144, v144, v145
	v_mov_b32_e32 v145, v144
	v_mov_b32_e32 v146, v144
	s_nop 1
	v_permlane32_swap_b32_e32 v145, v146
	s_and_saveexec_b64 s[22:23], s[0:1]
	s_cbranch_execz .LBB0_976
	v_cmp_eq_u32_e32 vcc, 0, v214
	v_max_f32_e32 v144, v144, v144
	s_nop 0
	v_cndmask_b32_e32 v145, v145, v146, vcc
	v_max_f32_e32 v145, v145, v145
	v_max_f32_e32 v144, v144, v145
	v_add_u32_e32 v145, s48, v176
	ds_write_b32 v145, v144
;     __device__ __forceinline__ void operator()(const Acc& acc, const Unit& u, int wr, int wc, int fr, int fq) const {
;     ...
;         for (int ai = 0; ai < 2; ++ai)
; #pragma unroll
;             for (int m = 0; m < 4; ++m) {
;                 const int rl = ai * 128 + wr * 64 + m * 16 + fr;
;                 rq[ai][m] = __builtin_amdgcn_rsqf(ssq[u.pm * 256 + rl] * (1.f / 256.f) + EPS) * (0.0625f * LOG2E);
;                 float v = -3.0e38f;
; #pragma unroll
;                 for (int bj = 0; bj < 2; ++bj)
; #pragma unroll
;                     for (int n = 0; n < 2; ++n)
; #pragma unroll
;                         for (int j = 0; j < 4; ++j) v = fmaxf(v, acc[ai][bj][m][n][j]);
;                 v *= rq[ai][m];
;                 v = fmaxf(v, xshfl<16>(v)); v = fmaxf(v, xshfl<32>(v));
;                 if (fq == 0) EXm[rl * 4 + wc] = v;
;             }
.LBB0_976:
	s_or_b64 exec, exec, s[22:23]
	v_max3_f32 v145, v60, s45, v61
	v_max3_f32 v145, v145, v62, v63
	v_max3_f32 v145, v145, v56, v57
	v_max3_f32 v145, v145, v58, v59
	v_max3_f32 v145, v145, v52, v53
	v_max3_f32 v145, v145, v54, v55
	v_max3_f32 v145, v145, v48, v49
	v_max3_f32 v145, v145, v50, v51
	s_waitcnt vmcnt(0)
	v_fmamk_f32 v144, v153, 0x3b800000, v212
	v_rsq_f32_e32 v144, v144
	s_nop 0
	v_mul_f32_e32 v153, 0x3db8aa3b, v144
	v_mul_f32_e32 v144, v145, v153
	ds_swizzle_b32 v145, v144 offset:swizzle(SWAP,16)
	s_waitcnt lgkmcnt(0)
	v_max_f32_e32 v145, v145, v145
	v_max_f32_e32 v144, v144, v145
	v_mov_b32_e32 v145, v144
	v_mov_b32_e32 v146, v144
	s_nop 1
	v_permlane32_swap_b32_e32 v145, v146
	s_and_saveexec_b64 s[22:23], s[0:1]
	s_cbranch_execz .LBB0_978
	v_cmp_eq_u32_e32 vcc, 0, v214
	v_max_f32_e32 v144, v144, v144
	s_nop 0
	v_cndmask_b32_e32 v145, v145, v146, vcc
	v_max_f32_e32 v145, v145, v145
	v_max_f32_e32 v144, v144, v145
	v_add_u32_e32 v145, s48, v178
	ds_write_b32 v145, v144
.LBB0_978:
	s_or_b64 exec, exec, s[22:23]
	v_max3_f32 v145, v44, s45, v45
	v_max3_f32 v145, v145, v46, v47
	v_max3_f32 v145, v145, v40, v41
	v_max3_f32 v145, v145, v42, v43
	v_max3_f32 v145, v145, v36, v37
	v_max3_f32 v145, v145, v38, v39
	v_max3_f32 v145, v145, v32, v33
	v_max3_f32 v145, v145, v34, v35
	s_waitcnt vmcnt(0)
	v_fmamk_f32 v144, v152, 0x3b800000, v212
	v_rsq_f32_e32 v144, v144
	s_nop 0
	v_mul_f32_e32 v152, 0x3db8aa3b, v144
	v_mul_f32_e32 v144, v145, v152
	ds_swizzle_b32 v145, v144 offset:swizzle(SWAP,16)
	s_waitcnt lgkmcnt(0)
	v_max_f32_e32 v145, v145, v145
	v_max_f32_e32 v144, v144, v145
	v_mov_b32_e32 v145, v144
	v_mov_b32_e32 v146, v144
	s_nop 1
	v_permlane32_swap_b32_e32 v145, v146
	s_and_saveexec_b64 s[22:23], s[0:1]
	s_cbranch_execz .LBB0_980
	v_cmp_eq_u32_e32 vcc, 0, v214
	v_max_f32_e32 v144, v144, v144
	s_nop 0
	v_cndmask_b32_e32 v145, v145, v146, vcc
	v_max_f32_e32 v145, v145, v145
	v_max_f32_e32 v144, v144, v145
	v_add_u32_e32 v145, s48, v180
	ds_write_b32 v145, v144
.LBB0_980:
	s_or_b64 exec, exec, s[22:23]
	v_max3_f32 v145, v28, s45, v29
	v_max3_f32 v145, v145, v30, v31
	v_max3_f32 v145, v145, v24, v25
	v_max3_f32 v145, v145, v26, v27
	v_max3_f32 v145, v145, v20, v21
	v_max3_f32 v145, v145, v22, v23
	v_max3_f32 v145, v145, v16, v17
	v_max3_f32 v145, v145, v18, v19
	s_waitcnt vmcnt(0)
	v_fmamk_f32 v144, v151, 0x3b800000, v212
	v_rsq_f32_e32 v144, v144
	s_nop 0
	v_mul_f32_e32 v151, 0x3db8aa3b, v144
	v_mul_f32_e32 v144, v145, v151
	ds_swizzle_b32 v145, v144 offset:swizzle(SWAP,16)
	s_waitcnt lgkmcnt(0)
	v_max_f32_e32 v145, v145, v145
	v_max_f32_e32 v144, v144, v145
	v_mov_b32_e32 v145, v144
	v_mov_b32_e32 v146, v144
	s_nop 1
	v_permlane32_swap_b32_e32 v145, v146
	s_and_saveexec_b64 s[22:23], s[0:1]
	s_cbranch_execz .LBB0_982
	v_cmp_eq_u32_e32 vcc, 0, v214
	v_max_f32_e32 v144, v144, v144
	s_nop 0
	v_cndmask_b32_e32 v145, v145, v146, vcc
	v_max_f32_e32 v145, v145, v145
	v_max_f32_e32 v144, v144, v145
	v_add_u32_e32 v145, s48, v182
	ds_write_b32 v145, v144
.LBB0_982:
	s_or_b64 exec, exec, s[22:23]
	v_max3_f32 v143, v12, s45, v13
	v_max3_f32 v143, v143, v14, v15
	v_max3_f32 v143, v143, v8, v9
	v_max3_f32 v143, v143, v10, v11
	v_max3_f32 v143, v143, v4, v5
	v_max3_f32 v143, v143, v6, v7
	v_max3_f32 v143, v143, v0, v1
	v_max3_f32 v143, v143, v2, v3
	s_waitcnt vmcnt(0)
	v_fmamk_f32 v142, v150, 0x3b800000, v212
	v_rsq_f32_e32 v142, v142
	s_nop 0
	v_mul_f32_e32 v150, 0x3db8aa3b, v142
	v_mul_f32_e32 v142, v143, v150
	ds_swizzle_b32 v143, v142 offset:swizzle(SWAP,16)
	s_waitcnt lgkmcnt(0)
	v_max_f32_e32 v143, v143, v143
	v_max_f32_e32 v142, v142, v143
	v_mov_b32_e32 v143, v142
	v_mov_b32_e32 v144, v142
	s_nop 1
	v_permlane32_swap_b32_e32 v143, v144
	s_and_saveexec_b64 s[22:23], s[0:1]
	s_cbranch_execz .LBB0_984
	v_cmp_eq_u32_e32 vcc, 0, v214
	v_max_f32_e32 v142, v142, v142
	s_nop 0
	v_cndmask_b32_e32 v143, v143, v144, vcc
	v_max_f32_e32 v143, v143, v143
	v_max_f32_e32 v142, v142, v143
	v_add_u32_e32 v143, s48, v184
	ds_write_b32 v143, v142
